# early GEMM epilogue stores write-through (sc1) to cut dirty-L2 flush at the grid barrier
# baseline (speedup 1.0000x reference)
.Lzb_skip:
	v_mad_i64_i32 v[168:169], s[2:3], v166, s9, v[158:159]
	v_lshl_add_u64 v[168:169], v[168:169], 0, v[160:161]
	s_and_b64 vcc, exec, s[4:5]
	s_mov_b32 s52, s8
	s_mov_b32 s40, s10
	s_mov_b64 s[42:43], s[12:13]
	s_waitcnt vmcnt(0)
	v_pk_add_f32 v[170:171], v[144:145], v[120:121]
	v_pk_add_f32 v[148:149], v[148:149], v[128:129]
	v_pk_add_f32 v[146:147], v[146:147], v[126:127]
	v_pk_add_f32 v[144:145], v[142:143], v[118:119]
	v_cvt_pk_bf16_f32 v142, v146, v147
	v_cvt_pk_bf16_f32 v143, v148, v149
	v_pk_add_f32 v[138:139], v[138:139], v[114:115]
	v_cvt_pk_bf16_f32 v144, v144, v145
	v_cvt_pk_bf16_f32 v145, v170, v171
	global_store_dwordx4 v[168:169], v[142:145], off sc1
	v_pk_add_f32 v[140:141], v[140:141], v[116:117]
	v_pk_add_f32 v[132:133], v[132:133], v[128:129]
	v_pk_add_f32 v[142:143], v[136:137], v[112:113]
	v_pk_add_f32 v[136:137], v[134:135], v[110:111]
	v_cvt_pk_bf16_f32 v134, v138, v139
	v_cvt_pk_bf16_f32 v135, v140, v141
	v_pk_add_f32 v[130:131], v[130:131], v[126:127]
	v_cvt_pk_bf16_f32 v136, v136, v137
	v_cvt_pk_bf16_f32 v137, v142, v143
	global_store_dwordx4 v[168:169], v[134:137], off offset:256 sc1
	v_pk_add_f32 v[106:107], v[106:107], v[114:115]
	v_pk_add_f32 v[108:109], v[108:109], v[116:117]
	v_or_b32_e32 v134, 16, v166
	v_mad_i64_i32 v[134:135], s[2:3], v134, s9, v[158:159]
	v_lshl_add_u64 v[134:135], v[134:135], 0, v[160:161]
	v_pk_add_f32 v[136:137], v[124:125], v[120:121]
	v_pk_add_f32 v[124:125], v[122:123], v[118:119]
	v_cvt_pk_bf16_f32 v122, v130, v131
	v_cvt_pk_bf16_f32 v123, v132, v133
	v_pk_add_f32 v[100:101], v[100:101], v[128:129]
	v_cvt_pk_bf16_f32 v124, v124, v125
	v_cvt_pk_bf16_f32 v125, v136, v137
	global_store_dwordx4 v[134:135], v[122:125], off sc1
	v_pk_add_f32 v[98:99], v[98:99], v[126:127]
	v_pk_add_f32 v[90:91], v[90:91], v[114:115]
	v_pk_add_f32 v[122:123], v[104:105], v[112:113]
	v_pk_add_f32 v[104:105], v[102:103], v[110:111]
	v_cvt_pk_bf16_f32 v102, v106, v107
	v_cvt_pk_bf16_f32 v103, v108, v109
	v_pk_add_f32 v[92:93], v[92:93], v[116:117]
	v_cvt_pk_bf16_f32 v104, v104, v105
	v_cvt_pk_bf16_f32 v105, v122, v123
	global_store_dwordx4 v[134:135], v[102:105], off offset:256 sc1
	v_pk_add_f32 v[84:85], v[84:85], v[128:129]
	v_pk_add_f32 v[82:83], v[82:83], v[126:127]
	v_or_b32_e32 v102, 32, v166
	v_mad_i64_i32 v[102:103], s[2:3], v102, s9, v[158:159]
	v_lshl_add_u64 v[102:103], v[102:103], 0, v[160:161]
	v_pk_add_f32 v[104:105], v[96:97], v[120:121]
	v_pk_add_f32 v[96:97], v[94:95], v[118:119]
	v_cvt_pk_bf16_f32 v94, v98, v99
	v_cvt_pk_bf16_f32 v95, v100, v101
	v_pk_add_f32 v[74:75], v[74:75], v[114:115]
	v_cvt_pk_bf16_f32 v96, v96, v97
	v_cvt_pk_bf16_f32 v97, v104, v105
	global_store_dwordx4 v[102:103], v[94:97], off sc1
	v_pk_add_f32 v[76:77], v[76:77], v[116:117]
	v_pk_add_f32 v[68:69], v[68:69], v[128:129]
	v_pk_add_f32 v[94:95], v[88:89], v[112:113]
	v_pk_add_f32 v[88:89], v[86:87], v[110:111]
	v_cvt_pk_bf16_f32 v86, v90, v91
	v_cvt_pk_bf16_f32 v87, v92, v93
	v_pk_add_f32 v[66:67], v[66:67], v[126:127]
	v_cvt_pk_bf16_f32 v88, v88, v89
	v_cvt_pk_bf16_f32 v89, v94, v95
	global_store_dwordx4 v[102:103], v[86:89], off offset:256 sc1
	v_pk_add_f32 v[58:59], v[58:59], v[114:115]
	v_pk_add_f32 v[60:61], v[60:61], v[116:117]
	v_or_b32_e32 v86, 48, v166
	v_mad_i64_i32 v[86:87], s[2:3], v86, s9, v[158:159]
	v_lshl_add_u64 v[86:87], v[86:87], 0, v[160:161]
	v_pk_add_f32 v[88:89], v[80:81], v[120:121]
	v_pk_add_f32 v[80:81], v[78:79], v[118:119]
	v_cvt_pk_bf16_f32 v78, v82, v83
	v_cvt_pk_bf16_f32 v79, v84, v85
	v_pk_add_f32 v[54:55], v[54:55], v[126:127]
	v_cvt_pk_bf16_f32 v80, v80, v81
	v_cvt_pk_bf16_f32 v81, v88, v89
	global_store_dwordx4 v[86:87], v[78:81], off sc1
	v_pk_add_f32 v[42:43], v[42:43], v[114:115]
	v_pk_add_f32 v[44:45], v[44:45], v[116:117]
	v_pk_add_f32 v[78:79], v[72:73], v[112:113]
	v_pk_add_f32 v[72:73], v[70:71], v[110:111]
	v_cvt_pk_bf16_f32 v70, v74, v75
	v_cvt_pk_bf16_f32 v71, v76, v77
	v_pk_add_f32 v[38:39], v[38:39], v[126:127]
	v_cvt_pk_bf16_f32 v72, v72, v73
	v_cvt_pk_bf16_f32 v73, v78, v79
	global_store_dwordx4 v[86:87], v[70:73], off offset:256 sc1
	v_pk_add_f32 v[26:27], v[26:27], v[114:115]
	v_pk_add_f32 v[28:29], v[28:29], v[116:117]
	v_add_u32_e32 v70, 0x80, v166
	v_mad_i64_i32 v[70:71], s[2:3], v70, s9, v[158:159]
	v_lshl_add_u64 v[70:71], v[70:71], 0, v[160:161]
	v_pk_add_f32 v[72:73], v[64:65], v[120:121]
	v_pk_add_f32 v[64:65], v[62:63], v[118:119]
	v_cvt_pk_bf16_f32 v62, v66, v67
	v_cvt_pk_bf16_f32 v63, v68, v69
	v_pk_add_f32 v[22:23], v[22:23], v[126:127]
	v_cvt_pk_bf16_f32 v64, v64, v65
	v_cvt_pk_bf16_f32 v65, v72, v73
	global_store_dwordx4 v[70:71], v[62:65], off sc1
	v_pk_add_f32 v[6:7], v[6:7], v[116:117]
	v_pk_add_f32 v[4:5], v[4:5], v[114:115]
	v_pk_add_f32 v[62:63], v[52:53], v[112:113]
	v_pk_add_f32 v[52:53], v[50:51], v[110:111]
	v_cvt_pk_bf16_f32 v50, v58, v59
	v_cvt_pk_bf16_f32 v51, v60, v61
	s_nop 0
	v_cvt_pk_bf16_f32 v52, v52, v53
	v_cvt_pk_bf16_f32 v53, v62, v63
	global_store_dwordx4 v[70:71], v[50:53], off offset:256 sc1
	s_nop 1
	v_add_u32_e32 v50, 0x90, v166
	v_mad_i64_i32 v[50:51], s[2:3], v50, s9, v[158:159]
	v_lshl_add_u64 v[50:51], v[50:51], 0, v[160:161]
	v_pk_add_f32 v[52:53], v[56:57], v[128:129]
	v_pk_add_f32 v[56:57], v[48:49], v[120:121]
	v_pk_add_f32 v[48:49], v[46:47], v[118:119]
	v_cvt_pk_bf16_f32 v46, v54, v55
	v_cvt_pk_bf16_f32 v47, v52, v53
	s_nop 0
	v_cvt_pk_bf16_f32 v48, v48, v49
	v_cvt_pk_bf16_f32 v49, v56, v57
	global_store_dwordx4 v[50:51], v[46:49], off sc1
	s_nop 1
	v_pk_add_f32 v[46:47], v[36:37], v[112:113]
	v_pk_add_f32 v[36:37], v[34:35], v[110:111]
	v_cvt_pk_bf16_f32 v34, v42, v43
	v_cvt_pk_bf16_f32 v35, v44, v45
	s_nop 0
	v_cvt_pk_bf16_f32 v36, v36, v37
	v_cvt_pk_bf16_f32 v37, v46, v47
	global_store_dwordx4 v[50:51], v[34:37], off offset:256 sc1
	s_nop 1
	v_add_u32_e32 v34, 0xa0, v166
	v_mad_i64_i32 v[34:35], s[2:3], v34, s9, v[158:159]
	v_lshl_add_u64 v[34:35], v[34:35], 0, v[160:161]
	v_pk_add_f32 v[36:37], v[40:41], v[128:129]
	v_pk_add_f32 v[40:41], v[32:33], v[120:121]
	v_pk_add_f32 v[32:33], v[30:31], v[118:119]
	v_cvt_pk_bf16_f32 v30, v38, v39
	v_cvt_pk_bf16_f32 v31, v36, v37
	s_nop 0
	v_cvt_pk_bf16_f32 v32, v32, v33
	v_cvt_pk_bf16_f32 v33, v40, v41
	global_store_dwordx4 v[34:35], v[30:33], off sc1
	s_nop 1
	v_pk_add_f32 v[30:31], v[20:21], v[112:113]
	v_pk_add_f32 v[20:21], v[18:19], v[110:111]
	v_cvt_pk_bf16_f32 v18, v26, v27
	v_cvt_pk_bf16_f32 v19, v28, v29
	s_nop 0
	v_cvt_pk_bf16_f32 v20, v20, v21
	v_cvt_pk_bf16_f32 v21, v30, v31
	global_store_dwordx4 v[34:35], v[18:21], off offset:256 sc1
	s_nop 1
	v_add_u32_e32 v18, 0xb0, v166
	v_mad_i64_i32 v[18:19], s[2:3], v18, s9, v[158:159]
	v_lshl_add_u64 v[18:19], v[18:19], 0, v[160:161]
	v_pk_add_f32 v[20:21], v[24:25], v[128:129]
	v_pk_add_f32 v[24:25], v[16:17], v[120:121]
	v_pk_add_f32 v[16:17], v[14:15], v[118:119]
	v_cvt_pk_bf16_f32 v14, v22, v23
	v_cvt_pk_bf16_f32 v15, v20, v21
	s_mov_b64 s[2:3], s[34:35]
	v_cvt_pk_bf16_f32 v16, v16, v17
	v_cvt_pk_bf16_f32 v17, v24, v25
	global_store_dwordx4 v[18:19], v[14:17], off sc1
	s_nop 1
	v_pk_add_f32 v[14:15], v[2:3], v[112:113]
	v_pk_add_f32 v[2:3], v[0:1], v[110:111]
	v_cvt_pk_bf16_f32 v0, v4, v5
	v_cvt_pk_bf16_f32 v1, v6, v7
	s_nop 0
	v_cvt_pk_bf16_f32 v2, v2, v3
	v_cvt_pk_bf16_f32 v3, v14, v15
	global_store_dwordx4 v[18:19], v[0:3], off offset:256 sc1
	s_cbranch_vccz .LBB0_721
	s_waitcnt vmcnt(0)
	s_cmpk_gt_u32 s19, 0xff
	s_cbranch_scc1 .LBB0_728
	s_barrier
